# DA K tile: conflict-free 16-way LDS swizzle (DMA source + ds_read sides) on top of rotated tile order
# speedup vs baseline: 1.0221x; 1.0004x over previous
; #define REP(k) for (int rep_ = 0; rep_ <= (int)(((REPMASK) >> (k)) & 1u); ++rep_)
; template <int DQK> __device__ __forceinline__ void qkt_acc(f32x16& p0, f32x16& p1, const char* Ks, const bf16x8* qr, int r32, int hi) {
;     ...
;   const int sw = (r32 & 7) << 4; const char* k0p = Ks + r32 * ROWB; const char* k1p = Ks + (32 + r32) * ROWB;
; #pragma unroll
;   for (int d0 = 0; d0 < DQK / 16; ++d0) { const int cb = ((d0 * 16 + hi * 8) * 2) ^ sw;
; __global__ void __launch_bounds__(512, 2) fwd_kernel(Params p) {
;     ...
;     if (IN(13)) REP(13) {
;         const int* pos = (const int*)p.in[1];
;         for (int it = vcu; it < 2048; it += G) {
;             const int q_ = it & 15, mp = (it >> 4) & 1, b = (it >> 5) & 7, h = it >> 8, qb = (q_ + ((h < 4) ? ((0x084C >> (4 * h)) & 15) : 0)) & 15; const size_t r0 = (size_t)b * SEQ;
;             att::AttnUnit U{};
;             U.Q = QKV1 + (r0 + qb * 256) * 6144 + h * 256 + mp * 128; U.K = QKV1 + r0 * 6144 + 2048 + h * 256 + mp * 128; U.V = QKV1 + r0 * 6144 + 4096 + h * 256;
;             U.O = O12 + (r0 + qb * 256) * 4096 + h * 512 + mp * 256;
;             U.ldq = 6144; U.ldk = 6144; U.ldv = 6144; U.ldo = 4096; U.jt0 = 0; U.NT = 64; U.q0 = qb * 256;
;             U.C = 0.08838834764831845f * LOG2E; U.thr = 8.0f / 0.08838834764831845f; U.posg = pos + r0; U.nsl = -exp2f(-(float)(h + 1)) * 11.313708498984761f;
.LBB0_1902:
	s_cmp_lt_i32 s92, 14
	s_cselect_b64 s[0:1], -1, 0
	s_cmp_gt_i32 s93, 13
	s_cselect_b64 s[2:3], -1, 0
	s_cmpk_lt_i32 s8, 0x800
	s_cselect_b64 s[4:5], -1, 0
	s_and_b64 s[0:1], s[0:1], s[4:5]
	s_and_b64 s[0:1], s[0:1], s[2:3]
	s_andn2_b64 vcc, exec, s[0:1]
	s_waitcnt lgkmcnt(0)
	s_barrier
	s_cbranch_vccnz .LBB0_1950
	s_waitcnt vmcnt(0)
	v_mbcnt_lo_u32_b32 v0, -1, 0
	s_lshl_b32 s11, s8, 7
	s_lshl_b32 s33, s96, 7
	v_mbcnt_hi_u32_b32 v235, -1, v0
	s_add_u32 s35, s30, 0x10fc2000
	v_and_b32_e32 v0, 64, v235
	s_addc_u32 s42, s31, 0
	s_mov_b32 s43, 0x42fc0000
	v_mov_b32_e32 v234, s89
	s_movk_i32 s48, 0x1800
	v_add_u32_e32 v236, 64, v0
	v_xor_b32_e32 v242, 32, v235
	s_movk_i32 s49, 0x1000
	s_movk_i32 s50, 0x1ff
	s_movk_i32 s51, 0x4000
	s_add_i32 s56, 0, 0x19000
	s_mov_b64 s[20:21], 0x800
	s_movk_i32 s57, 0xdff
	v_mov_b32_e32 v1, 0
	s_mov_b64 s[22:23], 0x100
	s_movk_i32 s58, 0x2000
	s_movk_i32 s59, 0x6000
	s_movk_i32 s60, 0xf0
	s_mov_b32 s61, 0xc3160000
	s_mov_b32 s62, 0x42b504f3
	s_branch .LBB0_1905

; __device__ __forceinline__ int v_rd_base(int lane) { return ((lane & 3) << 3) | (((lane >> 2) & 3) << 6) | (((lane >> 4) & 1) << 5) | (((lane >> 5) & 1) << 8); }
; #define WAIT_BAR_0() asm volatile("s_waitcnt vmcnt(0) lgkmcnt(0)\n\ts_barrier" ::: "memory")
; #define WAIT_BAR_0() asm volatile("s_waitcnt vmcnt(0) lgkmcnt(0)\n\ts_barrier" ::: "memory")
; #define WAIT_BAR_0() asm volatile("s_waitcnt vmcnt(0) lgkmcnt(0)\n\ts_barrier" ::: "memory")
; #define lane mk_lane()
; __device__ __forceinline__ void attn_unit_da(const AttnUnit& U, char* lds) {
;     ...
;   const unsigned kdst = lds0 + A_OFF_K + wid * 1024, vdst = lds0 + A_OFF_V + wid * 1024;
;   const int vb0 = (int)lds0 + A_OFF_V + v_rd_base(lane);
;   const long kstep = (long)KVBLK * U.ldk, vstep = (long)KVBLK * U.ldv;
;     ...
;   f32x16 p0, p1; float mn = 0.f, al = 1.f; bf16x8 pa0, pa1, pa2, pa3; const int NT = U.NT;
;   DMA_TILE(0, 0);
;   WAIT_BAR_0();
.LBB0_1934:
	s_or_b64 exec, exec, s[6:7]
	s_lshr_b32 s2, s8, 4
	s_and_b32 s2, s2, 1
	s_lshl_b32 s25, s2, 8
	s_mul_i32 s37, s37, 0x3000000
	s_lshl_b64 s[0:1], s[0:1], 1
	s_add_u32 s0, s37, s0
	s_addc_u32 s1, 0, s1
	s_add_u32 s0, s35, s0
	s_addc_u32 s1, s42, s1
	s_and_b32 s98, s66, 0xf00
	s_mul_i32 s98, s98, 0x3000
	s_add_u32 s0, s0, s98
	s_addc_u32 s1, s1, 0
	s_mulk_i32 s68, 0x3000
	s_add_u32 s2, s44, s68
	s_addc_u32 s3, s45, 0
	s_lshl_b32 s4, s24, 1
	s_add_u32 s5, s2, s18
	s_addc_u32 s6, s3, s19
	s_add_u32 s2, s5, s4
	s_addc_u32 s3, s6, 0
	s_add_u32 s2, s2, 0x1000
	s_addc_u32 s3, s3, 0
	s_add_u32 s4, s5, 0x2000
	s_addc_u32 s5, s6, 0
	s_add_u32 s2, s2, s98
	s_addc_u32 s3, s3, 0
	s_add_u32 s4, s4, s98
	s_addc_u32 s5, s5, 0
	s_lshl_b32 s6, s70, 2
	s_waitcnt lgkmcnt(1)
	v_mov_b32_e32 v6, v226
	s_add_i32 s24, s6, 0
	v_sub_u32_e32 v0, v0, v244
	s_add_i32 s24, s24, 0x18000
	v_bfe_u32 v8, v6, 4, 5
	v_cvt_f32_i32_e32 v130, v0
	s_lshl_b32 s37, s69, 10
	v_and_b32_e32 v0, 15, v6
	s_waitcnt lgkmcnt(0)
	v_lshrrev_b32_e32 v7, 4, v6
	v_lshlrev_b32_e32 v2, 2, v7
	v_bitop3_b32 v0, v2, v0, 12 bitop3:0x6c
	v_lshrrev_b32_e32 v2, 2, v7
	v_bitop3_b32 v0, v2, v0, 3 bitop3:0x6c
	v_mul_u32_u24_e32 v2, 0x1800, v8
	s_cmp_lg_u32 0, -1
	v_lshlrev_b32_e32 v2, 1, v2
	s_cselect_b32 s6, 0, 0
	v_lshl_or_b32 v0, v0, 4, v2
	s_add_i32 s37, s37, s6
	v_lshl_add_u64 v[2:3], s[2:3], 0, v[0:1]
	v_add_u32_e32 v0, 0x60000, v0
	s_add_i32 s38, s37, 0x10000
	s_mov_b32 s7, m0
	s_mov_b32 m0, s38
	s_nop 0
	global_load_lds_dwordx4 v[2:3], off
	s_mov_b32 m0, s7
	v_lshl_add_u64 v[2:3], s[2:3], 0, v[0:1]
	s_add_i32 s2, s37, 0x12000
	s_mov_b32 s3, m0
	s_mov_b32 m0, s2
	s_nop 0
	global_load_lds_dwordx4 v[2:3], off
	s_mov_b32 m0, s3
	v_and_b32_e32 v2, 0x60, v6
	v_lshlrev_b32_e32 v3, 3, v6
	v_and_or_b32 v9, v3, 24, v2
	v_lshrrev_b32_e32 v2, 1, v6
	v_lshrrev_b32_e32 v3, 5, v6
	v_bfe_u32 v0, v6, 2, 2
	v_and_b32_e32 v2, 8, v2
	v_and_b32_e32 v3, 4, v3
	v_or3_b32 v6, v3, v0, v2
	v_and_or_b32 v0, v7, 16, v6
	v_mul_u32_u24_e32 v0, 0x1800, v0
	v_or_b32_e32 v0, v0, v9
	v_or_b32_e32 v8, 32, v8
	v_lshlrev_b32_e32 v0, 1, v0
	v_lshl_add_u64 v[2:3], s[4:5], 0, v[0:1]
	v_and_or_b32 v0, v8, 48, v6
	v_mul_u32_u24_e32 v0, 0x1800, v0
	v_or_b32_e32 v0, v0, v9
	s_mov_b32 s2, m0
	s_mov_b32 m0, s37
	s_nop 0
	global_load_lds_dwordx4 v[2:3], off
	s_mov_b32 m0, s2
	v_lshl_add_u64 v[2:3], v[2:3], 0, s[22:23]
	v_lshlrev_b32_e32 v0, 1, v0
	s_add_i32 s2, s37, 0x4000
	s_mov_b32 s3, m0
	s_mov_b32 m0, s2
	s_nop 0
	global_load_lds_dwordx4 v[2:3], off
	s_mov_b32 m0, s3
	v_lshl_add_u64 v[2:3], s[4:5], 0, v[0:1]
	s_add_i32 s2, s37, 0x2000
	s_mov_b32 s3, m0
	s_mov_b32 m0, s2
	s_nop 0
	global_load_lds_dwordx4 v[2:3], off
	s_mov_b32 m0, s3
	v_lshl_add_u64 v[2:3], v[2:3], 0, s[22:23]
	s_add_i32 s2, s37, 0x6000
	s_mov_b32 s3, m0
	s_mov_b32 m0, s2
	s_nop 0
	global_load_lds_dwordx4 v[2:3], off
	s_mov_b32 m0, s3
	v_lshlrev_b32_e32 v2, 3, v243
	v_lshlrev_b32_e32 v3, 4, v243
	v_lshlrev_b32_e32 v239, 4, v5
	v_and_b32_e32 v6, 0xc0, v3
	v_and_b32_e32 v7, 0x118, v2
	v_lshlrev_b32_e32 v2, 2, v5
	v_lshlrev_b32_e32 v3, 6, v4
	v_and_b32_e32 v3, 0xc0, v3
	v_lshlrev_b32_e32 v14, 2, v4
	v_bitop3_b32 v3, v14, v3, 48 bitop3:0x6c
	v_add_u32_e32 v5, 32, v239
	v_bitop3_b32 v247, v5, v3, s60 bitop3:0x78
	v_add_u32_e32 v5, 64, v239
	v_bitop3_b32 v248, v5, v3, s60 bitop3:0x78
	v_add_u32_e32 v5, 0x60, v239
	v_bitop3_b32 v249, v5, v3, s60 bitop3:0x78
	v_add_u32_e32 v5, 0x80, v239
	v_bitop3_b32 v250, v5, v3, s60 bitop3:0x78
	v_add_u32_e32 v5, 0xa0, v239
	s_add_i32 s2, 0, 0x10000
	v_bitop3_b32 v252, v5, v3, s60 bitop3:0x78
	v_add_u32_e32 v5, 0xc0, v239
	v_lshlrev_b32_e32 v0, 1, v243
	v_bitop3_b32 v253, v5, v3, s60 bitop3:0x78
	v_add_u32_e32 v5, 0xe0, v239
	s_add_u32 s4, s54, s67
	v_bitop3_b32 v246, v3, v239, s60 bitop3:0x6c
	v_bitop3_b32 v254, v5, v3, s60 bitop3:0x78
	v_ashrrev_i32_e32 v3, 31, v2
	v_and_or_b32 v0, v0, 32, v7
	s_addc_u32 s5, s55, 0
	v_mov_b32_e32 v14, v1
	v_mov_b32_e32 v15, v1
	s_waitcnt vmcnt(0) lgkmcnt(0)
	s_barrier
; #define WAIT_BAR_0() asm volatile("s_waitcnt vmcnt(0) lgkmcnt(0)\n\ts_barrier" ::: "memory")
; #define WAIT_BAR_0() asm volatile("s_waitcnt vmcnt(0) lgkmcnt(0)\n\ts_barrier" ::: "memory")
; #define WAIT_BAR_0() asm volatile("s_waitcnt vmcnt(0) lgkmcnt(0)\n\ts_barrier" ::: "memory")
; __device__ __forceinline__ void attn_unit_da(const AttnUnit& U, char* lds) {
;     ...
;   float m_reg = -1e30f, l_reg = 0; f32x16 o[8] = {}; bf16x8 qr[ND0];
;     ...
;   f32x16 p0, p1; float mn = 0.f, al = 1.f; bf16x8 pa0, pa1, pa2, pa3; const int NT = U.NT;
;   DMA_TILE(0, 0);
;   WAIT_BAR_0();
;   for (int j = 0; j < NT; ++j) {
;     const int st = j & 1;
;     if (j + 1 < NT) DMA_TILE(j + 1, st ^ 1);
;     float rc;
;     { const int c_ = __builtin_amdgcn_readfirstlane(cls[j]); const float* ak_ = aux + j * KVBLK;
;       if (c_ < 2) { rc = (c_ == 0) ? pq * U.nsl : -pq * U.nsl;
	v_lshl_add_u32 v245, v4, 8, s2
	v_lshl_add_u32 v251, v4, 2, s24
	v_add3_u32 v237, v6, s6, v0
	v_lshl_add_u64 v[232:233], v[2:3], 2, s[4:5]
	v_mov_b32_e32 v0, v1
	v_mov_b32_e32 v2, v1
	v_mov_b32_e32 v3, v1
	v_mov_b32_e32 v4, v1
	v_mov_b32_e32 v5, v1
	v_mov_b32_e32 v6, v1
	v_mov_b32_e32 v7, v1
	v_mov_b32_e32 v8, v1
	v_mov_b32_e32 v9, v1
	v_mov_b32_e32 v10, v1
	v_mov_b32_e32 v11, v1
	v_mov_b32_e32 v12, v1
	v_mov_b32_e32 v13, v1
	v_mov_b64_e32 v[128:129], v[14:15]
	v_mov_b64_e32 v[112:113], v[14:15]
	v_mov_b64_e32 v[96:97], v[14:15]
	v_mov_b64_e32 v[80:81], v[14:15]
	v_mov_b64_e32 v[64:65], v[14:15]
	v_mov_b64_e32 v[48:49], v[14:15]
	v_mov_b64_e32 v[32:33], v[14:15]
	v_mov_b64_e32 v[126:127], v[12:13]
	v_mov_b64_e32 v[124:125], v[10:11]
	v_mov_b64_e32 v[122:123], v[8:9]
	v_mov_b64_e32 v[120:121], v[6:7]
	v_mov_b64_e32 v[118:119], v[4:5]
	v_mov_b64_e32 v[116:117], v[2:3]
	v_mov_b64_e32 v[114:115], v[0:1]
	v_mov_b64_e32 v[110:111], v[12:13]
	v_mov_b64_e32 v[108:109], v[10:11]
	v_mov_b64_e32 v[106:107], v[8:9]
	v_mov_b64_e32 v[104:105], v[6:7]
	v_mov_b64_e32 v[102:103], v[4:5]
	v_mov_b64_e32 v[100:101], v[2:3]
	v_mov_b64_e32 v[98:99], v[0:1]
	v_mov_b64_e32 v[94:95], v[12:13]
	v_mov_b64_e32 v[92:93], v[10:11]
	v_mov_b64_e32 v[90:91], v[8:9]
	v_mov_b64_e32 v[88:89], v[6:7]
	v_mov_b64_e32 v[86:87], v[4:5]
	v_mov_b64_e32 v[84:85], v[2:3]
	v_mov_b64_e32 v[82:83], v[0:1]
	v_mov_b64_e32 v[78:79], v[12:13]
	v_mov_b64_e32 v[76:77], v[10:11]
	v_mov_b64_e32 v[74:75], v[8:9]
	v_mov_b64_e32 v[72:73], v[6:7]
	v_mov_b64_e32 v[70:71], v[4:5]
	v_mov_b64_e32 v[68:69], v[2:3]
	v_mov_b64_e32 v[66:67], v[0:1]
	v_mov_b64_e32 v[62:63], v[12:13]
	v_mov_b64_e32 v[60:61], v[10:11]
	v_mov_b64_e32 v[58:59], v[8:9]
	v_mov_b64_e32 v[56:57], v[6:7]
	v_mov_b64_e32 v[54:55], v[4:5]
	v_mov_b64_e32 v[52:53], v[2:3]
	v_mov_b64_e32 v[50:51], v[0:1]
	v_mov_b64_e32 v[46:47], v[12:13]
	v_mov_b64_e32 v[44:45], v[10:11]
	v_mov_b64_e32 v[42:43], v[8:9]
	v_mov_b64_e32 v[40:41], v[6:7]
	v_mov_b64_e32 v[38:39], v[4:5]
	v_mov_b64_e32 v[36:37], v[2:3]
	v_mov_b64_e32 v[34:35], v[0:1]
	v_mov_b64_e32 v[30:31], v[12:13]
	v_mov_b64_e32 v[28:29], v[10:11]
	v_mov_b64_e32 v[26:27], v[8:9]
	v_mov_b64_e32 v[24:25], v[6:7]
	v_mov_b64_e32 v[22:23], v[4:5]
	v_mov_b64_e32 v[20:21], v[2:3]
	v_mov_b64_e32 v[18:19], v[0:1]
	v_mov_b64_e32 v[16:17], v[14:15]
	s_mov_b32 s36, 0
	v_cmp_gt_u32_e64 s[2:3], 32, v243
	v_mov_b32_e32 v230, v228
	v_mov_b32_e32 v231, v228
	v_mov_b32_e32 v131, v130
	v_mov_b32_e32 v132, v130
	v_mov_b32_e32 v133, v130
	v_mov_b32_e32 v134, v130
	v_mov_b32_e32 v135, v130
	v_mov_b32_e32 v136, v130
	v_mov_b32_e32 v137, v130
	v_mov_b32_e32 v138, v130
	v_mov_b32_e32 v139, v130
	v_mov_b32_e32 v140, v130
	v_mov_b32_e32 v141, v130
	v_mov_b32_e32 v142, v130
	v_mov_b32_e32 v240, 0
	v_mov_b32_e32 v238, 0xf149f2ca
	s_and_b32 s98, s66, 0xf00
	s_lshl_b32 s6, s98, 2
	s_mov_b32 s7, 0
	s_and_b32 s99, s66, 0xf00
	s_lshr_b32 s99, s99, 4
	s_add_i32 s39, s99, 0x1c800
	s_and_b32 s99, s66, 0xf00
	s_lshl_b32 s99, s99, 2
	v_add_u32_e32 v227, s99, v239
	v_mov_b32_e32 v143, v130
	v_mov_b32_e32 v144, v130
	v_mov_b32_e32 v145, v130
	v_mov_b64_e32 v[14:15], v[12:13]
	v_mov_b64_e32 v[12:13], v[10:11]
	v_mov_b64_e32 v[10:11], v[8:9]
	v_mov_b64_e32 v[8:9], v[6:7]
	v_mov_b64_e32 v[6:7], v[4:5]
	v_mov_b64_e32 v[4:5], v[2:3]
	v_mov_b64_e32 v[2:3], v[0:1]
	s_branch .LBB0_1938

; __device__ __forceinline__ void attn_unit_da(const AttnUnit& U, char* lds) {
;     ...
;   for (int j = 0; j < NT; ++j) {
;     const int st = j & 1;
;     if (j + 1 < NT) DMA_TILE(j + 1, st ^ 1);
.LBB0_1938:
	s_and_b32 s40, s36, 1
	s_cmp_gt_u32 s36, 62
	s_cbranch_scc1 .LBB0_1940
	v_mov_b32_e32 v148, v226
	s_add_u32 s4, s0, s25
	s_addc_u32 s5, s1, 0
	v_bfe_u32 v150, v148, 4, 5
	v_and_b32_e32 v0, 15, v148
	v_lshrrev_b32_e32 v149, 4, v148
	v_mul_u32_u24_e32 v146, 0x1800, v150
	s_add_u32 s4, s4, 0xfffff000
	v_lshlrev_b32_e32 v151, 2, v149
	v_bitop3_b32 v0, v151, v0, 12 bitop3:0x6c
	v_lshrrev_b32_e32 v151, 2, v149
	v_bitop3_b32 v0, v151, v0, 3 bitop3:0x6c
	v_lshlrev_b32_e32 v146, 1, v146
	s_addc_u32 s5, s5, -1
	s_lshl_b32 s18, s40, 14
	v_lshl_or_b32 v0, v0, 4, v146
	s_xor_b32 s18, s18, 0x4000
	v_lshl_add_u64 v[146:147], s[4:5], 0, v[0:1]
	v_add_u32_e32 v0, 0x60000, v0
	s_add_i32 s18, s18, s38
	s_mov_b32 s19, m0
	s_mov_b32 m0, s18
	s_nop 0
	global_load_lds_dwordx4 v[146:147], off
	s_mov_b32 m0, s19
	v_lshl_add_u64 v[146:147], s[4:5], 0, v[0:1]
	s_add_i32 s4, s18, 0x2000
	s_mov_b32 s5, m0
	s_mov_b32 m0, s4
	s_nop 0
	global_load_lds_dwordx4 v[146:147], off
	s_mov_b32 m0, s5
	v_lshlrev_b32_e32 v146, 3, v148
	v_and_b32_e32 v152, 24, v146
	v_lshrrev_b32_e32 v146, 1, v148
	v_lshrrev_b32_e32 v147, 5, v148
	v_bfe_u32 v0, v148, 2, 2
	v_and_b32_e32 v146, 8, v146
	v_and_b32_e32 v147, 4, v147
	v_and_b32_e32 v151, 0x60, v148
	v_or3_b32 v148, v147, v0, v146
	v_and_or_b32 v0, v149, 16, v148
	v_mul_u32_u24_e32 v0, 0x1800, v0
	v_or_b32_e32 v150, 32, v150
	s_lshl_b32 s4, s40, 15
	v_or3_b32 v0, v0, v151, v152
	s_xor_b32 s4, s4, 0x8000
	v_lshl_add_u64 v[146:147], v[0:1], 1, s[0:1]
	v_and_or_b32 v0, v150, 48, v148
	s_add_i32 s4, s4, s37
	s_mov_b32 s5, m0
	s_mov_b32 m0, s4
	s_nop 0
	global_load_lds_dwordx4 v[146:147], off
	s_mov_b32 m0, s5
	v_mul_u32_u24_e32 v0, 0x1800, v0
	v_lshl_add_u64 v[146:147], v[146:147], 0, s[22:23]
	s_add_i32 s5, s4, 0x4000
	s_mov_b32 s18, m0
	s_mov_b32 m0, s5
	s_nop 0
	global_load_lds_dwordx4 v[146:147], off
	s_mov_b32 m0, s18
	v_or3_b32 v0, v0, v151, v152
	v_lshl_add_u64 v[146:147], v[0:1], 1, s[0:1]
	s_add_i32 s5, s4, 0x2000
	s_mov_b32 s18, m0
	s_mov_b32 m0, s5
	s_nop 0
	global_load_lds_dwordx4 v[146:147], off
	s_mov_b32 m0, s18
	v_lshl_add_u64 v[146:147], v[146:147], 0, s[22:23]
	s_addk_i32 s4, 0x6000
	s_mov_b32 s5, m0
	s_mov_b32 m0, s4
	s_nop 0
	global_load_lds_dwordx4 v[146:147], off
	s_mov_b32 m0, s5
